# MoBA fast path: V transpose-reads issued before the rare-path decision (fills the max/permlane/compare/branch latency)
# baseline (speedup 1.0000x reference)
.Lm_fastA:
	ds_read_b128 v[196:199], v179
	ds_read_b128 v[200:203], v179 offset:512
	ds_read_b128 v[204:207], v179 offset:2080
	ds_read_b128 v[208:211], v179 offset:2592
	ds_read_b128 v[212:215], v179 offset:4160
	ds_read_b128 v[216:219], v179 offset:4672
	ds_read_b128 v[188:191], v179 offset:6240
	ds_read_b128 v[224:227], v179 offset:6752
	v_max_f32_e32 v238, v32, v32
	v_max_f32_e32 v239, v48, v48
	v_max3_f32 v238, v238, v33, v34
	v_max3_f32 v239, v239, v49, v50
	v_max3_f32 v238, v238, v35, v36
	s_waitcnt lgkmcnt(7)
	v_mfma_f32_32x32x16_bf16 v[64:79], v[196:199], v[128:131], 0
	v_max3_f32 v239, v239, v51, v52
	v_max3_f32 v238, v238, v37, v38
	v_max3_f32 v239, v239, v53, v54
	v_max3_f32 v238, v238, v39, v40
	s_waitcnt lgkmcnt(6)
	v_mfma_f32_32x32x16_bf16 v[80:95], v[200:203], v[128:131], 0
	v_max3_f32 v239, v239, v55, v56
	v_max3_f32 v238, v238, v41, v42
	v_max3_f32 v239, v239, v57, v58
	v_max3_f32 v238, v238, v43, v44
	s_waitcnt lgkmcnt(5)
	v_mfma_f32_32x32x16_bf16 v[64:79], v[204:207], v[132:135], v[64:79]
	v_max3_f32 v239, v239, v59, v60
	v_max3_f32 v238, v238, v45, v46
	v_max3_f32 v239, v239, v61, v62
	s_waitcnt lgkmcnt(4)
	v_mfma_f32_32x32x16_bf16 v[80:95], v[208:211], v[132:135], v[80:95]
	v_max3_f32 v238, v238, v47, v63
	v_max_f32_e32 v238, v238, v239
	v_mov_b32_e32 v239, v238
	s_waitcnt lgkmcnt(0)
	ds_read_b64_tr_b16 v[196:197], v178 offset:49920
	ds_read_b64_tr_b16 v[198:199], v178 offset:50432
	ds_read_b64_tr_b16 v[200:201], v178 offset:54016
	ds_read_b64_tr_b16 v[202:203], v178 offset:54528
	ds_read_b64_tr_b16 v[204:205], v178 offset:50944
	ds_read_b64_tr_b16 v[206:207], v178 offset:51456
	ds_read_b64_tr_b16 v[208:209], v178 offset:55040
	ds_read_b64_tr_b16 v[210:211], v178 offset:55552
	v_permlane32_swap_b32_e32 v238, v239
	v_max_f32_e32 v238, v238, v239
	v_cmp_lt_f32_e32 vcc, s1, v238
	s_cbranch_vccnz .Lm_rareA
	v_exp_f32_e32 v32, v32
	v_exp_f32_e32 v48, v48
	v_exp_f32_e32 v33, v33
	v_exp_f32_e32 v49, v49
	v_mfma_f32_32x32x16_bf16 v[64:79], v[212:215], v[136:139], v[64:79]
	v_exp_f32_e32 v34, v34
	v_exp_f32_e32 v50, v50
	v_exp_f32_e32 v35, v35
	v_exp_f32_e32 v51, v51
	v_exp_f32_e32 v36, v36
	v_exp_f32_e32 v52, v52
	v_mfma_f32_32x32x16_bf16 v[80:95], v[216:219], v[136:139], v[80:95]
	v_exp_f32_e32 v37, v37
	v_exp_f32_e32 v53, v53
	v_exp_f32_e32 v38, v38
	v_exp_f32_e32 v54, v54
	v_exp_f32_e32 v39, v39
	v_exp_f32_e32 v55, v55
	v_mfma_f32_32x32x16_bf16 v[64:79], v[188:191], v[140:143], v[64:79]
	v_exp_f32_e32 v40, v40
	v_exp_f32_e32 v56, v56
	v_exp_f32_e32 v41, v41
	v_exp_f32_e32 v57, v57
	v_exp_f32_e32 v42, v42
	v_exp_f32_e32 v58, v58
	v_mfma_f32_32x32x16_bf16 v[80:95], v[224:227], v[140:143], v[80:95]
	v_exp_f32_e32 v43, v43
	v_exp_f32_e32 v59, v59
	v_exp_f32_e32 v44, v44
	v_exp_f32_e32 v60, v60
	v_exp_f32_e32 v45, v45
	v_exp_f32_e32 v61, v61
	v_exp_f32_e32 v46, v46
	v_exp_f32_e32 v62, v62
	v_exp_f32_e32 v47, v47
	v_exp_f32_e32 v63, v63
	s_waitcnt lgkmcnt(7)
	ds_read_b64_tr_b16 v[212:213], v178 offset:51968
	ds_read_b64_tr_b16 v[214:215], v178 offset:52480
	ds_read_b64_tr_b16 v[216:217], v178 offset:56064
	ds_read_b64_tr_b16 v[218:219], v178 offset:56576
	ds_read_b64_tr_b16 v[188:189], v178 offset:52992
	ds_read_b64_tr_b16 v[190:191], v178 offset:53504
	ds_read_b64_tr_b16 v[224:225], v178 offset:57088
	ds_read_b64_tr_b16 v[226:227], v178 offset:57600
	v_add_f32_e32 v238, v52, v36
	v_add_f32_e32 v239, v53, v37
	v_add_f32_e32 v240, v48, v32
	v_add_f32_e32 v241, v49, v33
	v_add_f32_e32 v242, v54, v38
	v_add_f32_e32 v243, v55, v39
	v_add_f32_e32 v244, v50, v34
	v_add_f32_e32 v245, v51, v35
	s_mov_b64 exec, s[6:7]
	v_cvt_pk_bf16_f32 v156, v32, v33
	v_cvt_pk_bf16_f32 v157, v34, v35
	v_cvt_pk_bf16_f32 v158, v36, v37
	v_cvt_pk_bf16_f32 v159, v38, v39
	s_mov_b64 exec, -1
	v_add_f32_e32 v246, v58, v42
	v_add_f32_e32 v247, v59, v43
	v_add_f32_e32 v248, v56, v40
	v_add_f32_e32 v249, v57, v41
	s_waitcnt lgkmcnt(14)
	v_mfma_f32_32x32x16_bf16 v[16:31], v[156:159], v[196:199], v[16:31]
	v_add_f32_e32 v242, v244, v242
	v_add_f32_e32 v243, v245, v243
	v_add_f32_e32 v238, v240, v238
	v_add_f32_e32 v239, v241, v239
	s_mov_b64 exec, s[6:7]
	v_cvt_pk_bf16_f32 v152, v40, v41
	v_cvt_pk_bf16_f32 v153, v42, v43
	v_cvt_pk_bf16_f32 v154, v44, v45
	v_cvt_pk_bf16_f32 v155, v46, v47
	s_mov_b64 exec, -1
	s_waitcnt lgkmcnt(12)
	v_mfma_f32_32x32x16_bf16 v[0:15], v[156:159], v[200:203], v[0:15]
	v_add_f32_e32 v240, v60, v44
	v_add_f32_e32 v241, v61, v45
	v_add_f32_e32 v244, v62, v46
	v_add_f32_e32 v245, v63, v47
	s_waitcnt lgkmcnt(10)
	v_mfma_f32_32x32x16_bf16 v[16:31], v[152:155], v[204:207], v[16:31]
	v_add_f32_e32 v248, v248, v238
	v_add_f32_e32 v249, v249, v239
	v_add_f32_e32 v246, v246, v242
	v_add_f32_e32 v247, v247, v243
	s_mov_b64 exec, s[6:7]
	v_cvt_pk_bf16_f32 v148, v48, v49
	v_cvt_pk_bf16_f32 v149, v50, v51
	v_cvt_pk_bf16_f32 v150, v52, v53
	v_cvt_pk_bf16_f32 v151, v54, v55
	s_mov_b64 exec, -1
	s_waitcnt lgkmcnt(8)
	v_mfma_f32_32x32x16_bf16 v[0:15], v[152:155], v[208:211], v[0:15]
	v_add_f32_e32 v182, v240, v248
	v_add_f32_e32 v183, v241, v249
	v_add_f32_e32 v180, v244, v246
	v_add_f32_e32 v181, v245, v247
	s_waitcnt lgkmcnt(6)
	v_mfma_f32_32x32x16_bf16 v[16:31], v[148:151], v[212:215], v[16:31]
	v_pk_mov_b32 v[184:185], v[182:183], v[180:181] op_sel:[1,0]
	v_mov_b32_e32 v183, v181
	s_mov_b64 exec, s[6:7]
	v_cvt_pk_bf16_f32 v144, v56, v57
	v_cvt_pk_bf16_f32 v145, v58, v59
	v_cvt_pk_bf16_f32 v146, v60, v61
	v_cvt_pk_bf16_f32 v147, v62, v63
	s_mov_b64 exec, -1
	s_waitcnt lgkmcnt(4)
	v_mfma_f32_32x32x16_bf16 v[0:15], v[148:151], v[216:219], v[0:15]
	v_add_f32_e32 v180, v184, v182
	v_add_f32_e32 v181, v185, v183
	s_waitcnt lgkmcnt(2)
	v_mfma_f32_32x32x16_bf16 v[16:31], v[144:147], v[188:191], v[16:31]
	v_add_f32_e32 v181, v180, v181
	v_cndmask_b32_e64 v181, 0, v181, s[6:7]
	v_add_f32_e32 v177, v177, v181
	s_waitcnt lgkmcnt(0)
	v_mfma_f32_32x32x16_bf16 v[0:15], v[144:147], v[224:227], v[0:15]
	v_add_u32_e32 v180, 0, v178
	s_andn2_b64 s[8:9], exec, s[54:55]
	s_branch .Lm_halfB

.Lm_fastB:
	v_add_u32_e32 v251, 0x10100, v178
	ds_read_b128 v[196:199], v179 offset:8320
	ds_read_b128 v[200:203], v179 offset:8832
	ds_read_b128 v[204:207], v179 offset:10400
	ds_read_b128 v[208:211], v179 offset:10912
	ds_read_b128 v[212:215], v179 offset:12480
	ds_read_b128 v[216:219], v179 offset:12992
	ds_read_b128 v[188:191], v179 offset:14560
	ds_read_b128 v[224:227], v179 offset:15072
	v_max_f32_e32 v238, v64, v64
	v_max_f32_e32 v239, v80, v80
	v_max3_f32 v238, v238, v65, v66
	v_max3_f32 v239, v239, v81, v82
	v_max3_f32 v238, v238, v67, v68
	s_waitcnt lgkmcnt(7)
	v_mfma_f32_32x32x16_bf16 v[32:47], v[196:199], v[128:131], 0
	v_max3_f32 v239, v239, v83, v84
	v_max3_f32 v238, v238, v69, v70
	v_max3_f32 v239, v239, v85, v86
	v_max3_f32 v238, v238, v71, v72
	s_waitcnt lgkmcnt(6)
	v_mfma_f32_32x32x16_bf16 v[48:63], v[200:203], v[128:131], 0
	v_max3_f32 v239, v239, v87, v88
	v_max3_f32 v238, v238, v73, v74
	v_max3_f32 v239, v239, v89, v90
	v_max3_f32 v238, v238, v75, v76
	s_waitcnt lgkmcnt(5)
	v_mfma_f32_32x32x16_bf16 v[32:47], v[204:207], v[132:135], v[32:47]
	v_max3_f32 v239, v239, v91, v92
	v_max3_f32 v238, v238, v77, v78
	v_max3_f32 v239, v239, v93, v94
	s_waitcnt lgkmcnt(4)
	v_mfma_f32_32x32x16_bf16 v[48:63], v[208:211], v[132:135], v[48:63]
	v_max3_f32 v238, v238, v79, v95
	v_max_f32_e32 v238, v238, v239
	v_mov_b32_e32 v239, v238
	s_waitcnt lgkmcnt(0)
	ds_read_b64_tr_b16 v[196:197], v178 offset:58112
	ds_read_b64_tr_b16 v[198:199], v178 offset:58624
	ds_read_b64_tr_b16 v[200:201], v178 offset:62208
	ds_read_b64_tr_b16 v[202:203], v178 offset:62720
	ds_read_b64_tr_b16 v[204:205], v178 offset:59136
	ds_read_b64_tr_b16 v[206:207], v178 offset:59648
	ds_read_b64_tr_b16 v[208:209], v178 offset:63232
	ds_read_b64_tr_b16 v[210:211], v178 offset:63744
	v_permlane32_swap_b32_e32 v238, v239
	v_max_f32_e32 v238, v238, v239
	v_cmp_lt_f32_e32 vcc, s1, v238
	s_cbranch_vccnz .Lm_rareB
	v_exp_f32_e32 v64, v64
	v_exp_f32_e32 v80, v80
	v_exp_f32_e32 v65, v65
	v_exp_f32_e32 v81, v81
	v_mfma_f32_32x32x16_bf16 v[32:47], v[212:215], v[136:139], v[32:47]
	v_exp_f32_e32 v66, v66
	v_exp_f32_e32 v82, v82
	v_exp_f32_e32 v67, v67
	v_exp_f32_e32 v83, v83
	v_exp_f32_e32 v68, v68
	v_exp_f32_e32 v84, v84
	v_mfma_f32_32x32x16_bf16 v[48:63], v[216:219], v[136:139], v[48:63]
	v_exp_f32_e32 v69, v69
	v_exp_f32_e32 v85, v85
	v_exp_f32_e32 v70, v70
	v_exp_f32_e32 v86, v86
	v_exp_f32_e32 v71, v71
	v_exp_f32_e32 v87, v87
	v_mfma_f32_32x32x16_bf16 v[32:47], v[188:191], v[140:143], v[32:47]
	v_exp_f32_e32 v72, v72
	v_exp_f32_e32 v88, v88
	v_exp_f32_e32 v73, v73
	v_exp_f32_e32 v89, v89
	v_exp_f32_e32 v74, v74
	v_exp_f32_e32 v90, v90
	v_mfma_f32_32x32x16_bf16 v[48:63], v[224:227], v[140:143], v[48:63]
	v_exp_f32_e32 v75, v75
	v_exp_f32_e32 v91, v91
	v_exp_f32_e32 v76, v76
	v_exp_f32_e32 v92, v92
	v_exp_f32_e32 v77, v77
	v_exp_f32_e32 v93, v93
	v_exp_f32_e32 v78, v78
	v_exp_f32_e32 v94, v94
	v_exp_f32_e32 v79, v79
	v_exp_f32_e32 v95, v95
	s_waitcnt lgkmcnt(7)
	ds_read_b64_tr_b16 v[212:213], v178 offset:60160
	ds_read_b64_tr_b16 v[214:215], v178 offset:60672
	ds_read_b64_tr_b16 v[216:217], v178 offset:64256
	ds_read_b64_tr_b16 v[218:219], v178 offset:64768
	ds_read_b64_tr_b16 v[188:189], v178 offset:61184
	ds_read_b64_tr_b16 v[190:191], v178 offset:61696
	ds_read_b64_tr_b16 v[224:225], v178 offset:65280
	ds_read_b64_tr_b16 v[226:227], v251
	v_add_f32_e32 v238, v84, v68
	v_add_f32_e32 v239, v85, v69
	v_add_f32_e32 v240, v80, v64
	v_add_f32_e32 v241, v81, v65
	v_add_f32_e32 v242, v86, v70
	v_add_f32_e32 v243, v87, v71
	v_add_f32_e32 v244, v82, v66
	v_add_f32_e32 v245, v83, v67
	s_mov_b64 exec, s[6:7]
	v_cvt_pk_bf16_f32 v156, v64, v65
	v_cvt_pk_bf16_f32 v157, v66, v67
	v_cvt_pk_bf16_f32 v158, v68, v69
	v_cvt_pk_bf16_f32 v159, v70, v71
	s_mov_b64 exec, -1
	v_add_f32_e32 v246, v90, v74
	v_add_f32_e32 v247, v91, v75
	v_add_f32_e32 v248, v88, v72
	v_add_f32_e32 v249, v89, v73
	s_waitcnt lgkmcnt(14)
	v_mfma_f32_32x32x16_bf16 v[16:31], v[156:159], v[196:199], v[16:31]
	v_add_f32_e32 v242, v244, v242
	v_add_f32_e32 v243, v245, v243
	v_add_f32_e32 v238, v240, v238
	v_add_f32_e32 v239, v241, v239
	s_mov_b64 exec, s[6:7]
	v_cvt_pk_bf16_f32 v152, v72, v73
	v_cvt_pk_bf16_f32 v153, v74, v75
	v_cvt_pk_bf16_f32 v154, v76, v77
	v_cvt_pk_bf16_f32 v155, v78, v79
	s_mov_b64 exec, -1
	s_waitcnt lgkmcnt(12)
	v_mfma_f32_32x32x16_bf16 v[0:15], v[156:159], v[200:203], v[0:15]
	v_add_f32_e32 v240, v92, v76
	v_add_f32_e32 v241, v93, v77
	v_add_f32_e32 v244, v94, v78
	v_add_f32_e32 v245, v95, v79
	s_waitcnt lgkmcnt(10)
	v_mfma_f32_32x32x16_bf16 v[16:31], v[152:155], v[204:207], v[16:31]
	v_add_f32_e32 v248, v248, v238
	v_add_f32_e32 v249, v249, v239
	v_add_f32_e32 v246, v246, v242
	v_add_f32_e32 v247, v247, v243
	s_mov_b64 exec, s[6:7]
	v_cvt_pk_bf16_f32 v148, v80, v81
	v_cvt_pk_bf16_f32 v149, v82, v83
	v_cvt_pk_bf16_f32 v150, v84, v85
	v_cvt_pk_bf16_f32 v151, v86, v87
	s_mov_b64 exec, -1
	s_waitcnt lgkmcnt(8)
	v_mfma_f32_32x32x16_bf16 v[0:15], v[152:155], v[208:211], v[0:15]
	v_add_f32_e32 v184, v240, v248
	v_add_f32_e32 v185, v241, v249
	v_add_f32_e32 v182, v244, v246
	v_add_f32_e32 v183, v245, v247
	s_waitcnt lgkmcnt(6)
	v_mfma_f32_32x32x16_bf16 v[16:31], v[148:151], v[212:215], v[16:31]
	v_pk_mov_b32 v[186:187], v[184:185], v[182:183] op_sel:[1,0]
	v_mov_b32_e32 v185, v183
	s_mov_b64 exec, s[6:7]
	v_cvt_pk_bf16_f32 v144, v88, v89
	v_cvt_pk_bf16_f32 v145, v90, v91
	v_cvt_pk_bf16_f32 v146, v92, v93
	v_cvt_pk_bf16_f32 v147, v94, v95
	s_mov_b64 exec, -1
	s_waitcnt lgkmcnt(4)
	v_mfma_f32_32x32x16_bf16 v[0:15], v[148:151], v[216:219], v[0:15]
	v_add_f32_e32 v182, v186, v184
	v_add_f32_e32 v183, v187, v185
	s_waitcnt lgkmcnt(2)
	v_mfma_f32_32x32x16_bf16 v[16:31], v[144:147], v[188:191], v[16:31]
	v_add_f32_e32 v181, v182, v183
	v_cndmask_b32_e64 v181, 0, v181, s[6:7]
	v_add_f32_e32 v177, v177, v181
	s_waitcnt lgkmcnt(0)
	v_mfma_f32_32x32x16_bf16 v[0:15], v[144:147], v[224:227], v[0:15]
	v_add_u32_e32 v179, 0x4100, v179
	v_add_u32_e32 v178, 0x4000, v178
	s_add_i32 s71, s71, 2
	s_addk_i32 s70, 0x80
	s_branch .LBB0_349
